# attention work-queue tail reordered: the 64 shortest MLA units are popped before the 128 shortest FoX units
# baseline (speedup 1.0000x reference)
; __global__ void __launch_bounds__(512, 2) fwd_kernel(Args a) {
;     ...
;         for (;;) {
;             if (tid == 0) *qw = atomicAdd(ctl + 64 * rep, 1u);
;             __syncthreads();
;             const unsigned idx = *qw;
;             __syncthreads();
;             if (idx >= 768u) break;
;             const int level = idx / 48, rr = idx % 48, qb = 15 - level;
.Ldq_tail:
	s_sub_i32 s6, s6, 0x300
	s_cmp_lt_u32 s6, 64
	s_cbranch_scc0 .Ldq_tfox
	s_lshr_b32 s0, s6, 4
	s_and_b32 s8, s6, 15
	s_branch .Ldq_tdone
.Ldq_tfox:
	s_sub_i32 s6, s6, 64
	s_lshr_b32 s0, s6, 5
	s_and_b32 s8, s6, 31
	s_add_i32 s8, s8, 16
.Ldq_tdone:
	s_add_i32 s0, s0, 12
	s_sub_i32 s39, 15, s0
	s_mul_i32 s1, s0, 48
	s_add_i32 s6, s1, s8
	s_branch .Ldq_done2

; #define LAS __attribute__((address_space(3)))
; template <int DQK, int DV, bool FOX> ...
;     ...
;     const int tid = threadIdx.x, lane = tid & 63, r = lane & 31, h = lane >> 5; const int w = __builtin_amdgcn_readfirstlane(tid >> 6);
;     const int q0 = qb * 256;
;     const int NT = 4 * qb + 4, ntw = 4 * qb + (w >> 1) + 1;
;     LAS float* wsf = (LAS float*)(lds + WS_OFF) + w * 64;
;     bf16x8 qf[ND0];
;     { const bf16_t* qp = Q + (size_t)(q0 + 32 * w + r) * ldq + 8 * h;
; #pragma unroll
;       for (int d0 = 0; d0 < ND0; ++d0) qf[d0] = *(const bf16x8*)(qp + 16 * d0); }
;     float cq = 0.f, basev = 0.f;
;     if (FOX) {
;         const float tv = tot[lane]; float incl = tv;
; #pragma unroll
;         for (int o_ = 1; o_ < 64; o_ <<= 1) { const float t_ = __shfl_up(incl, o_); if (lane >= o_) incl += t_; }
;         basev = incl - tv;
;         cq = cum[q0 + 32 * w + r] + __builtin_bit_cast(float, __builtin_amdgcn_readlane(__builtin_bit_cast(int, basev), 4 * qb + (w >> 1)));
;     }
.Ldq_done2:
	s_mov_b64 s[0:1], -1
	s_cmp_gt_u32 s8, 15
	v_lshlrev_b32_e32 v150, 1, v148
	v_lshlrev_b32_e32 v190, 1, v154
	s_cbranch_scc0 .LBB0_679
	s_add_i32 s84, s8, -16
	s_lshr_b32 s0, s84, 4
	s_mov_b32 s1, s85
	v_writelane_b32 v255, s0, 44
	v_mov_b32_e32 v5, v151
	v_and_b32_e32 v105, 64, v228
	v_writelane_b32 v255, s1, 45
	s_lshl_b64 s[0:1], s[0:1], 26
	v_readlane_b32 s2, v255, 16
	s_add_u32 s0, s2, s0
	v_readlane_b32 s2, v255, 17
	s_addc_u32 s1, s2, s1
	s_lshl_b32 s2, s8, 6
	s_and_b32 s2, s2, 0x3c0
	s_lshl_b32 s2, s2, 1
	v_writelane_b32 v255, s2, 46
	s_add_u32 s14, s0, s2
	s_addc_u32 s15, s1, 0
	s_lshl_b64 s[0:1], s[84:85], 14
	v_readlane_b32 s2, v255, 12
	s_add_u32 s16, s2, s0
	v_readlane_b32 s2, v255, 13
	s_addc_u32 s17, s2, s1
	v_readlane_b32 s2, v255, 22
	s_add_u32 s2, s2, s0
	v_readlane_b32 s0, v255, 23
	s_addc_u32 s3, s0, s1
	s_lshl_b32 s84, s84, 6
	v_lshl_add_u64 v[2:3], s[84:85], 2, v[152:153]
	global_load_dword v3, v[2:3], off
	v_readfirstlane_b32 s1, v0
	s_lshr_b32 s7, s1, 6
	s_lshl_b32 s0, s39, 8
	s_lshl_b32 s4, s7, 5
	s_add_i32 s0, s4, s0
	v_or_b32_e32 v4, s0, v146
	v_lshlrev_b64 v[8:9], 14, v[4:5]
	v_lshl_add_u64 v[4:5], v[4:5], 2, s[16:17]
	v_lshl_add_u64 v[8:9], s[14:15], 0, v[8:9]
	global_load_dword v10, v[4:5], off
	v_lshl_add_u64 v[4:5], v[8:9], 0, v[150:151]
	global_load_dwordx4 v[66:69], v[4:5], off
	global_load_dwordx4 v[70:73], v[4:5], off offset:32
	global_load_dwordx4 v[74:77], v[4:5], off offset:64
	global_load_dwordx4 v[78:81], v[4:5], off offset:96
	v_add_u32_e32 v6, -1, v228
	v_add_u32_e32 v11, -2, v228
	v_cmp_lt_i32_e32 vcc, v6, v105
	v_add_u32_e32 v12, -4, v228
	v_add_u32_e32 v13, -8, v228
	v_cndmask_b32_e32 v4, v6, v228, vcc
	v_cmp_lt_i32_e32 vcc, v11, v105
	v_add_u32_e32 v14, -16, v228
	v_subrev_u32_e32 v15, 32, v228
	v_cndmask_b32_e32 v5, v11, v228, vcc
	v_cmp_lt_i32_e32 vcc, v12, v105
	s_and_b32 s16, s1, 0xffffffc0
	s_lshr_b32 s9, s1, 2
	v_cndmask_b32_e32 v6, v12, v228, vcc
	v_cmp_lt_i32_e32 vcc, v13, v105
	v_lshlrev_b32_e32 v12, 2, v4
	v_and_or_b32 v4, s9, 48, v155
	v_cndmask_b32_e32 v8, v13, v228, vcc
	v_cmp_lt_i32_e32 vcc, v14, v105
	v_mov_b32_e32 v7, v151
	v_lshlrev_b32_e32 v13, 2, v5
	v_cndmask_b32_e32 v9, v14, v228, vcc
	v_cmp_lt_i32_e32 vcc, v15, v105
	v_lshlrev_b32_e32 v14, 2, v6
	v_lshlrev_b32_e32 v6, 14, v4
	v_cndmask_b32_e32 v11, v15, v228, vcc
	v_or_b32_e32 v15, s16, v196
	v_ashrrev_i32_e32 v5, 31, v15
	v_lshrrev_b32_e32 v16, 29, v5
	v_lshl_add_u64 v[4:5], s[14:15], 0, v[6:7]
	s_mov_b64 s[18:19], 0x1000
	v_lshl_add_u64 v[4:5], v[4:5], 0, s[18:19]
	v_readlane_b32 s18, v255, 24
	v_readlane_b32 s19, v255, 25
	v_lshlrev_b32_e32 v8, 2, v8
	v_add_u32_e32 v7, v15, v16
	v_lshlrev_b32_e32 v9, 2, v9
	v_lshlrev_b32_e32 v11, 2, v11
	s_lshr_b32 s17, s1, 3
	s_lshl_b32 s33, s7, 10
	s_lshl_b32 s5, s39, 2
	s_lshr_b32 s11, s1, 7
	s_and_b32 s7, s17, 0x1fffffe0
	s_add_i32 s33, s33, 0
	s_add_i32 s11, s11, s5
	s_lshl_b32 s84, s7, 1
	s_add_i32 s9, s33, 0x2000
	s_mov_b64 s[20:21], 0x800
	s_cmp_lt_u32 s1, 64
	v_mov_b32_e32 v191, v151
	v_lshl_add_u64 v[4:5], v[4:5], 0, s[84:85]
	s_cselect_b64 s[96:97], -1, 0
	s_cmp_gt_u32 s1, 63
	v_lshl_add_u64 v[4:5], v[4:5], 0, v[190:191]
	s_cselect_b64 s[92:93], -1, 0
	v_lshlrev_b32_e32 v2, 2, v196
	s_and_b64 vcc, exec, s[92:93]
	s_waitcnt vmcnt(5)
	ds_bpermute_b32 v6, v12, v3
	s_waitcnt lgkmcnt(0)
	v_add_f32_e32 v6, v3, v6
	v_cndmask_b32_e64 v12, v6, v3, s[18:19]
	ds_bpermute_b32 v13, v13, v12
	v_readlane_b32 s18, v255, 26
	v_readlane_b32 s19, v255, 27
	v_ashrrev_i32_e32 v6, 3, v7
	v_and_b32_e32 v7, 0x1ffffff8, v7
	s_waitcnt lgkmcnt(0)
	v_add_f32_e32 v13, v12, v13
	v_cndmask_b32_e64 v12, v13, v12, s[18:19]
	ds_bpermute_b32 v13, v14, v12
	v_readlane_b32 s18, v255, 28
	v_readlane_b32 s19, v255, 29
	v_sub_u32_e32 v14, v15, v7
	v_lshrrev_b32_e32 v15, 1, v6
	s_waitcnt lgkmcnt(0)
	v_add_f32_e32 v13, v12, v13
	v_cndmask_b32_e64 v12, v13, v12, s[18:19]
	ds_bpermute_b32 v8, v8, v12
	v_readlane_b32 s18, v255, 30
	v_readlane_b32 s19, v255, 31
	v_bitop3_b32 v13, v15, v14, 7 bitop3:0x6c
	v_ashrrev_i32_e32 v7, 31, v6
	s_waitcnt lgkmcnt(0)
	v_add_f32_e32 v8, v12, v8
	v_cndmask_b32_e64 v12, v8, v12, s[18:19]
	ds_bpermute_b32 v14, v9, v12
	v_lshlrev_b64 v[6:7], 14, v[6:7]
	v_lshl_add_u64 v[6:7], s[14:15], 0, v[6:7]
	v_readlane_b32 s14, v255, 32
	v_lshlrev_b32_e32 v8, 3, v13
	s_waitcnt lgkmcnt(0)
	v_add_f32_e32 v13, v12, v14
	v_readlane_b32 s15, v255, 33
	v_ashrrev_i32_e32 v9, 31, v8
	v_lshl_add_u64 v[8:9], v[8:9], 1, v[6:7]
	v_cndmask_b32_e64 v12, v13, v12, s[14:15]
	ds_bpermute_b32 v11, v11, v12
	v_lshl_add_u64 v[6:7], v[8:9], 0, s[20:21]
	s_mov_b32 s1, m0
	s_mov_b32 m0, s33
	s_nop 0
	global_load_lds_dwordx4 v[6:7], off
	s_mov_b32 m0, s1
	s_waitcnt lgkmcnt(0)
	v_add_f32_e32 v11, v12, v11
	s_mov_b32 s1, m0
	s_mov_b32 m0, s9
	s_nop 0
	global_load_lds_dwordx4 v[4:5], off
	s_mov_b32 m0, s1
	v_cndmask_b32_e64 v11, v11, v12, s[12:13]
	v_sub_f32_e32 v107, v11, v3
	s_nop 0
	v_readlane_b32 s17, v107, s11
	s_cbranch_vccnz .LBB0_651
	v_mov_b32_e32 v3, v151
	v_lshl_add_u64 v[12:13], s[2:3], 0, v[2:3]
	v_readlane_b32 s7, v255, 34
	s_mov_b32 s1, m0
	s_mov_b32 m0, s7
	s_nop 0
	global_load_lds_dword v[12:13], off
	s_mov_b32 m0, s1
